# MoBA spread LDS writes wait twice instead of eight times, no-op base add dropped, compute test evaluated once
# baseline (speedup 1.0000x reference)
.Lms_inter:
	v_mov_b32_e32 v198, v197
	s_nop 1
	v_permlane16_swap_b32_e32 v197, v198
	v_max_f32_e32 v197, v197, v198
	v_mov_b32_e32 v198, v197
	s_nop 1
	v_permlane32_swap_b32_e32 v197, v198
	v_max3_f32 v197, v196, v197, v198
	v_cmp_neq_f32_e32 vcc, s73, v197
	s_nop 1
	v_cndmask_b32_e32 v198, 0, v197, vcc
	v_sub_f32_e32 v196, v196, v198
	v_mul_f32_e32 v199, 0x3e0293ee, v196
	v_mul_f32_e32 v196, 0xbe0293ee, v198
	v_cndmask_b32_e64 v198, v196, v215, s[0:1]
	v_fmamk_f32 v112, v112, 0x3e0293ee, v198
	v_exp_f32_e32 v112, v112
	v_fmamk_f32 v113, v113, 0x3e0293ee, v198
	s_xor_b32 s87, s15, 1
	v_exp_f32_e32 v113, v113
	v_fmamk_f32 v114, v114, 0x3e0293ee, v198
	s_mul_i32 s87, s87, 0x11000
	v_exp_f32_e32 v114, v114
	v_fmamk_f32 v115, v115, 0x3e0293ee, v198
	v_exp_f32_e32 v115, v115
	v_add3_u32 v224, s87, v165, v216
	v_fmamk_f32 v108, v108, 0x3e0293ee, v198
	v_add_f32_e32 v196, 0, v112
	v_add3_u32 v223, s87, v0, v216
	v_exp_f32_e32 v108, v108
	v_fmamk_f32 v109, v109, 0x3e0293ee, v198
	v_add_f32_e32 v196, v113, v196
	v_add_u32_e32 v225, 0x8800, v224
	v_exp_f32_e32 v109, v109
	v_fmamk_f32 v110, v110, 0x3e0293ee, v198
	s_waitcnt vmcnt(4)
	v_add_f32_e32 v196, v114, v196
	v_exp_f32_e32 v110, v110
	v_fmamk_f32 v111, v111, 0x3e0293ee, v198
	ds_write_b128 v223, v[4:7]
	v_add_f32_e32 v196, v115, v196
	v_exp_f32_e32 v111, v111
	ds_write2_b64 v225, v[8:9], v[10:11] offset1:2
	v_fmamk_f32 v104, v104, 0x3e0293ee, v198
	v_add_f32_e32 v196, v108, v196
	ds_write_b128 v223, v[12:15] offset:8704
	v_exp_f32_e32 v104, v104
	v_fmamk_f32 v105, v105, 0x3e0293ee, v198
	v_add_f32_e32 v196, v109, v196
	v_add_u32_e32 v225, 0xa800, v224
	v_exp_f32_e32 v105, v105
	v_fmamk_f32 v106, v106, 0x3e0293ee, v198
	ds_write2_b64 v225, v[16:17], v[18:19] offset0:64 offset1:66
	v_add_f32_e32 v196, v110, v196
	v_exp_f32_e32 v106, v106
	v_fmamk_f32 v107, v107, 0x3e0293ee, v198
	s_waitcnt vmcnt(0)
	v_add_f32_e32 v196, v111, v196
	v_exp_f32_e32 v107, v107
	ds_write_b128 v223, v[20:23] offset:17408
	v_fmamk_f32 v100, v100, 0x3e0293ee, v198
	v_add_f32_e32 v196, v104, v196
	v_exp_f32_e32 v100, v100
	v_add_u32_e32 v225, 0xc800, v224
	v_fmamk_f32 v101, v101, 0x3e0293ee, v198
	v_add_f32_e32 v196, v105, v196
	ds_write2_b64 v225, v[24:25], v[26:27] offset0:128 offset1:130
	v_exp_f32_e32 v101, v101
	v_fmamk_f32 v102, v102, 0x3e0293ee, v198
	v_add_f32_e32 v196, v106, v196
	ds_write_b128 v223, v[28:31] offset:26112
	v_exp_f32_e32 v102, v102
	v_fmamk_f32 v103, v103, 0x3e0293ee, v198
	v_add_u32_e32 v223, 0xe800, v224
	v_add_f32_e32 v196, v107, v196
	v_exp_f32_e32 v103, v103
	ds_write2_b64 v223, v[32:33], v[34:35] offset0:192 offset1:194
	s_andn2_b64 vcc, exec, s[80:81]
	s_cbranch_vccnz .Lms_t2plain
	v_fmamk_f32 v96, v96, 0x3e0293ee, v198
	v_add_f32_e32 v196, v100, v196
	s_lshr_b32 s82, s14, 1
	v_exp_f32_e32 v96, v96
	v_fmamk_f32 v97, v97, 0x3e0293ee, v198
	s_sub_i32 s82, s47, s82
	v_add_f32_e32 v196, v101, v196
	v_exp_f32_e32 v97, v97
	s_lshl_b32 s83, s14, 7
	v_fmamk_f32 v98, v98, 0x3e0293ee, v198
	s_lshl_b32 s82, s82, 8
	v_add_f32_e32 v196, v102, v196
	v_exp_f32_e32 v98, v98
	s_and_b32 s83, s83, 0x80
	v_fmamk_f32 v99, v99, 0x3e0293ee, v198
	v_add_f32_e32 v196, v103, v196
	s_or_b32 s82, s82, s83
	v_exp_f32_e32 v99, v99
	v_fmamk_f32 v92, v92, 0x3e0293ee, v198
	s_ashr_i32 s83, s82, 31
	v_add_f32_e32 v196, v96, v196
	v_lshl_add_u64 v[28:29], s[82:83], 1, v[118:119]
	v_exp_f32_e32 v92, v92
	v_fmamk_f32 v93, v93, 0x3e0293ee, v198
	s_mul_i32 s82, s82, s72
	v_add_f32_e32 v196, v97, v196
	v_exp_f32_e32 v93, v93
	s_add_u32 s82, s82, s3
	v_fmamk_f32 v94, v94, 0x3e0293ee, v198
	v_add_f32_e32 v196, v98, v196
	s_mov_b32 s83, 0
	v_exp_f32_e32 v94, v94
	v_lshl_add_u64 v[4:5], v[250:251], 0, s[82:83]
	v_fmamk_f32 v95, v95, 0x3e0293ee, v198
	v_add_f32_e32 v196, v99, v196
	v_lshl_add_u64 v[8:9], v[28:29], 0, v[146:147]
	v_exp_f32_e32 v95, v95
	v_fmamk_f32 v88, v88, 0x3e0293ee, v198
	s_add_u32 s82, s82, 0x3c000
	v_add_f32_e32 v196, v92, v196
	v_lshl_add_u64 v[12:13], v[250:251], 0, s[82:83]
	v_exp_f32_e32 v88, v88
	v_fmamk_f32 v89, v89, 0x3e0293ee, v198
	v_lshl_add_u64 v[16:17], v[28:29], 0, v[148:149]
	v_add_f32_e32 v196, v93, v196
	v_exp_f32_e32 v89, v89
	s_add_u32 s82, s82, 0x3c000
	v_fmamk_f32 v90, v90, 0x3e0293ee, v198
	v_add_f32_e32 v196, v94, v196
	v_lshl_add_u64 v[20:21], v[250:251], 0, s[82:83]
	v_exp_f32_e32 v90, v90
	v_lshl_add_u64 v[24:25], v[28:29], 0, v[150:151]
	v_fmamk_f32 v91, v91, 0x3e0293ee, v198
	v_add_f32_e32 v196, v95, v196
	s_add_u32 s82, s82, 0x3c000
	v_exp_f32_e32 v91, v91
	v_add_f32_e32 v196, v88, v196
	v_lshl_add_u64 v[30:31], v[250:251], 0, s[82:83]
	v_add_f32_e32 v196, v89, v196
	v_add_f32_e32 v196, v90, v196
	v_lshl_add_u64 v[32:33], v[28:29], 0, v[152:153]
	v_fmamk_f32 v84, v84, 0x3e0293ee, v198
	global_load_dwordx4 v[4:7], v[4:5], off offset:1024
	v_add_f32_e32 v200, v91, v196
	v_exp_f32_e32 v196, v84
	global_load_dwordx4 v[8:11], v[8:9], off
	v_fmamk_f32 v85, v85, 0x3e0293ee, v198
	v_exp_f32_e32 v85, v85
	global_load_dwordx4 v[12:15], v[12:13], off offset:1024
	v_fmamk_f32 v86, v86, 0x3e0293ee, v198
	v_exp_f32_e32 v86, v86
	global_load_dwordx4 v[16:19], v[16:17], off
	v_fmac_f32_e32 v198, 0x3e0293ee, v87
	global_load_dwordx4 v[20:23], v[20:21], off offset:1024
	v_exp_f32_e32 v87, v198
	v_add_f32_e32 v84, v196, v200
	global_load_dwordx4 v[24:27], v[24:25], off
	v_add_f32_e32 v84, v85, v84
	v_add_f32_e32 v84, v86, v84
	global_load_dwordx4 v[28:31], v[30:31], off offset:1024
	v_add_f32_e32 v198, v87, v84
	global_load_dwordx4 v[32:35], v[32:33], off
	s_branch .Lms_join
